# B1 step 6: the three conv-history ushort loads no longer serialized behind full waits; converted after the x loads (on v029)
# baseline (speedup 1.0000x reference)
; DI float bf2f(bf16_t b) { return __uint_as_float(((unsigned)b) << 16); }
; DI void phaseB1(const Params& p, int l, char* smem) {
;     ...
;       if (tid < 128) {
;         const int ch = 1024 + hd * 128 + tid;
;         const float w0 = convw[ch], w1 = convw[1536 + ch], w2 = convw[2 * 1536 + ch], w3 = convw[3 * 1536 + ch];
;         const bf16_t* src = p.projB + (size_t)tok0 * LDA_B + ch;
;         float x0 = 0.f, x1 = 0.f, x2 = 0.f;
;         if (n > 0) { x0 = bf2f(src[-3 * LDA_B]); x1 = bf2f(src[-2 * LDA_B]); x2 = bf2f(src[-1 * LDA_B]); }
.LBB0_1944:
	s_andn2_saveexec_b64 s[88:89], s[88:89]
	s_cbranch_execz .LBB0_1949
	v_add_u32_e32 v0, 0x400, v163
	v_add_u32_e32 v2, s2, v0
	v_ashrrev_i32_e32 v3, 31, v2
	v_lshl_add_u64 v[4:5], v[2:3], 2, s[0:1]
	v_add_co_u32_e32 v6, vcc, 0x1000, v4
	global_load_dword v0, v[4:5], off
	s_nop 0
	v_addc_co_u32_e32 v7, vcc, 0, v5, vcc
	global_load_dword v60, v[6:7], off offset:2048
	v_add_co_u32_e32 v6, vcc, 0x3000, v4
	v_readlane_b32 s16, v252, 57
	s_nop 0
	v_addc_co_u32_e32 v7, vcc, 0, v5, vcc
	global_load_dword v62, v[6:7], off
	v_add_co_u32_e32 v4, vcc, 0x4000, v4
	s_mul_hi_i32 s3, s35, 0xc00
	s_nop 0
	v_addc_co_u32_e32 v5, vcc, 0, v5, vcc
	global_load_dword v64, v[4:5], off offset:2048
	s_mulk_i32 s35, 0xc00
	v_readlane_b32 s26, v253, 3
	v_readlane_b32 s27, v253, 4
	s_add_u32 s2, s26, s35
	s_addc_u32 s3, s27, s3
	v_lshl_add_u64 v[2:3], v[2:3], 1, s[2:3]
	s_cmp_eq_u32 s34, 0
	v_readlane_b32 s17, v252, 58
	v_readlane_b32 s18, v252, 59
	v_readlane_b32 s19, v252, 60
	v_readlane_b32 s20, v252, 61
	v_readlane_b32 s21, v252, 62
	v_readlane_b32 s22, v252, 63
	v_readlane_b32 s23, v253, 0
	v_readlane_b32 s24, v253, 1
	v_readlane_b32 s25, v253, 2
	v_readlane_b32 s28, v253, 5
	v_readlane_b32 s29, v253, 6
	v_readlane_b32 s30, v253, 7
	v_readlane_b32 s31, v253, 8
	s_cbranch_scc1 .LBB0_1947
	v_add_co_u32_e32 v4, vcc, 0xffffe000, v2
	s_nop 1
	v_addc_co_u32_e32 v5, vcc, -1, v3, vcc
	global_load_ushort v58, v[4:5], off offset:-1024
	v_add_co_u32_e32 v4, vcc, 0xfffff000, v2
	s_nop 1
	v_addc_co_u32_e32 v5, vcc, -1, v3, vcc
	global_load_ushort v59, v[4:5], off offset:-2048
	s_nop 0
	global_load_ushort v67, v[2:3], off offset:-3072
	s_branch .LBB0_1948

; DI float bf2f(bf16_t b) { return __uint_as_float(((unsigned)b) << 16); }
; DI void phaseB1(const Params& p, int l, char* smem) {
;     ...
;         const bf16_t* src = p.projB + (size_t)tok0 * LDA_B + ch;
;         float x0 = 0.f, x1 = 0.f, x2 = 0.f;
;         if (n > 0) { x0 = bf2f(src[-3 * LDA_B]); x1 = bf2f(src[-2 * LDA_B]); x2 = bf2f(src[-1 * LDA_B]); }
; #pragma unroll
;         for (int i = 0; i < 64; ++i) x[i] = bf2f(src[(size_t)i * LDA_B]);
.LBB0_1948:
	v_add_co_u32_e32 v6, vcc, 0x2c000, v2
	global_load_ushort v4, v[2:3], off
	s_nop 0
	v_addc_co_u32_e32 v7, vcc, 0, v3, vcc
	v_add_co_u32_e32 v8, vcc, 0x2d000, v2
	global_load_ushort v5, v[6:7], off offset:1024
	s_nop 0
	v_addc_co_u32_e32 v9, vcc, 0, v3, vcc
	global_load_ushort v7, v[8:9], off
	global_load_ushort v6, v[8:9], off offset:3072
	v_add_co_u32_e32 v8, vcc, 0x2e000, v2
	s_mov_b32 s2, 0x20000
	s_nop 0
	v_addc_co_u32_e32 v9, vcc, 0, v3, vcc
	v_add_co_u32_e32 v10, vcc, 0x2f000, v2
	global_load_ushort v8, v[8:9], off offset:2048
	s_nop 0
	v_addc_co_u32_e32 v11, vcc, 0, v3, vcc
	v_add_co_u32_e32 v14, vcc, 0x2a000, v2
	s_waitcnt vmcnt(4)
	v_lshlrev_b32_e32 v69, 16, v4
	v_addc_co_u32_e32 v15, vcc, 0, v3, vcc
	v_add_co_u32_e32 v12, vcc, 0x2b000, v2
	s_nop 1
	v_addc_co_u32_e32 v13, vcc, 0, v3, vcc
	v_add_co_u32_e32 v16, vcc, 0x29000, v2
	global_load_ushort v12, v[12:13], off offset:2048
	s_nop 0
	v_addc_co_u32_e32 v17, vcc, 0, v3, vcc
	v_add_co_u32_e32 v18, vcc, 0x27000, v2
	global_load_ushort v9, v[10:11], off offset:1024
	s_nop 0
	v_addc_co_u32_e32 v19, vcc, 0, v3, vcc
	global_load_ushort v10, v[14:15], off offset:3072
	global_load_ushort v11, v[16:17], off offset:1024
	global_load_ushort v13, v[14:15], off
	v_add_co_u32_e32 v16, vcc, 0x28000, v2
	global_load_ushort v14, v[18:19], off offset:3072
	s_nop 0
	v_addc_co_u32_e32 v17, vcc, 0, v3, vcc
	global_load_ushort v15, v[16:17], off offset:2048
	v_add_co_u32_e32 v16, vcc, 0x26000, v2
	s_nop 1
	v_addc_co_u32_e32 v17, vcc, 0, v3, vcc
	v_add_co_u32_e32 v22, vcc, 0x24000, v2
	global_load_ushort v16, v[16:17], off offset:1024
	s_nop 0
	global_load_ushort v17, v[18:19], off
	v_addc_co_u32_e32 v23, vcc, 0, v3, vcc
	v_add_co_u32_e32 v20, vcc, 0x25000, v2
	global_load_ushort v18, v[22:23], off offset:3072
	s_nop 0
	v_addc_co_u32_e32 v21, vcc, 0, v3, vcc
	v_add_co_u32_e32 v24, vcc, 0x23000, v2
	global_load_ushort v20, v[20:21], off offset:2048
	s_nop 0
	v_addc_co_u32_e32 v25, vcc, 0, v3, vcc
	v_add_co_u32_e32 v26, vcc, 0x21000, v2
	global_load_ushort v19, v[24:25], off offset:1024
	global_load_ushort v21, v[22:23], off
	v_addc_co_u32_e32 v27, vcc, 0, v3, vcc
	v_add_co_u32_e32 v24, vcc, 0x22000, v2
	global_load_ushort v22, v[26:27], off offset:3072
	s_nop 0
	v_addc_co_u32_e32 v25, vcc, 0, v3, vcc
	global_load_ushort v23, v[24:25], off offset:2048
	v_add_co_u32_e32 v24, vcc, s2, v2
	s_mov_b32 s2, 0x10000
	s_nop 0
	v_addc_co_u32_e32 v25, vcc, 0, v3, vcc
	v_add_co_u32_e32 v30, vcc, 0x1e000, v2
	global_load_ushort v24, v[24:25], off offset:1024
	s_nop 0
	global_load_ushort v25, v[26:27], off
	v_addc_co_u32_e32 v31, vcc, 0, v3, vcc
	v_add_co_u32_e32 v28, vcc, 0x1f000, v2
	global_load_ushort v26, v[30:31], off offset:3072
	s_nop 0
	v_addc_co_u32_e32 v29, vcc, 0, v3, vcc
	v_add_co_u32_e32 v32, vcc, 0x1d000, v2
	global_load_ushort v28, v[28:29], off offset:2048
	s_nop 0
	v_addc_co_u32_e32 v33, vcc, 0, v3, vcc
	v_add_co_u32_e32 v34, vcc, 0x1b000, v2
	global_load_ushort v27, v[32:33], off offset:1024
	global_load_ushort v29, v[30:31], off
	v_addc_co_u32_e32 v35, vcc, 0, v3, vcc
	v_add_co_u32_e32 v32, vcc, 0x1c000, v2
	global_load_ushort v30, v[34:35], off offset:3072
	s_nop 0
	v_addc_co_u32_e32 v33, vcc, 0, v3, vcc
	global_load_ushort v31, v[32:33], off offset:2048
	v_add_co_u32_e32 v32, vcc, 0x1a000, v2
	s_nop 1
	v_addc_co_u32_e32 v33, vcc, 0, v3, vcc
	v_add_co_u32_e32 v38, vcc, 0x18000, v2
	global_load_ushort v32, v[32:33], off offset:1024
	s_nop 0
	global_load_ushort v33, v[34:35], off
	v_addc_co_u32_e32 v39, vcc, 0, v3, vcc
	v_add_co_u32_e32 v36, vcc, 0x19000, v2
	global_load_ushort v34, v[38:39], off offset:3072
	s_nop 0
	v_addc_co_u32_e32 v37, vcc, 0, v3, vcc
	v_add_co_u32_e32 v40, vcc, 0x17000, v2
	global_load_ushort v36, v[36:37], off offset:2048
	s_nop 0
	v_addc_co_u32_e32 v41, vcc, 0, v3, vcc
	v_add_co_u32_e32 v42, vcc, 0x15000, v2
	global_load_ushort v35, v[40:41], off offset:1024
	global_load_ushort v37, v[38:39], off
	v_addc_co_u32_e32 v43, vcc, 0, v3, vcc
	v_add_co_u32_e32 v40, vcc, 0x16000, v2
	global_load_ushort v38, v[42:43], off offset:3072
	s_nop 0
	v_addc_co_u32_e32 v41, vcc, 0, v3, vcc
	global_load_ushort v39, v[40:41], off offset:2048
	v_add_co_u32_e32 v40, vcc, 0x14000, v2
	s_nop 1
	v_addc_co_u32_e32 v41, vcc, 0, v3, vcc
	v_add_co_u32_e32 v46, vcc, 0x12000, v2
	global_load_ushort v40, v[40:41], off offset:1024
	s_nop 0
	global_load_ushort v41, v[42:43], off
	v_addc_co_u32_e32 v47, vcc, 0, v3, vcc
	v_add_co_u32_e32 v44, vcc, 0x13000, v2
	global_load_ushort v42, v[46:47], off offset:3072
	s_nop 0
	v_addc_co_u32_e32 v45, vcc, 0, v3, vcc
	v_add_co_u32_e32 v48, vcc, 0x11000, v2
	global_load_ushort v44, v[44:45], off offset:2048
	s_nop 0
	v_addc_co_u32_e32 v49, vcc, 0, v3, vcc
	global_load_ushort v43, v[48:49], off offset:1024
	global_load_ushort v45, v[46:47], off
	v_add_co_u32_e32 v46, vcc, 0xf000, v2
	s_nop 1
	v_addc_co_u32_e32 v47, vcc, 0, v3, vcc
	v_add_co_u32_e32 v48, vcc, s2, v2
	s_mov_b32 s2, 0xe000
	s_nop 0
	v_addc_co_u32_e32 v49, vcc, 0, v3, vcc
	global_load_ushort v50, v[46:47], off offset:3072
	global_load_ushort v51, v[48:49], off offset:2048
	v_add_co_u32_e32 v48, vcc, s2, v2
	s_mov_b32 s2, 0xc000
	s_nop 0
	v_addc_co_u32_e32 v49, vcc, 0, v3, vcc
	global_load_ushort v52, v[48:49], off offset:1024
	global_load_ushort v53, v[46:47], off
	v_add_co_u32_e32 v46, vcc, s2, v2
	s_mov_b32 s2, 0xd000
	s_nop 0
	v_addc_co_u32_e32 v47, vcc, 0, v3, vcc
	v_add_co_u32_e32 v48, vcc, s2, v2
	s_mov_b32 s2, 0xb000
	s_nop 0
	v_addc_co_u32_e32 v49, vcc, 0, v3, vcc
	global_load_ushort v54, v[46:47], off offset:3072
	global_load_ushort v55, v[48:49], off offset:2048
	v_add_co_u32_e32 v48, vcc, s2, v2
; DI float bf2f(bf16_t b) { return __uint_as_float(((unsigned)b) << 16); }
; DI float siluf(float x) { return x * __builtin_amdgcn_rcpf(1.f + __expf(-x)); }
; DI void phaseB1(const Params& p, int l, char* smem) {
;     ...
;         if (n > 0) { x0 = bf2f(src[-3 * LDA_B]); x1 = bf2f(src[-2 * LDA_B]); x2 = bf2f(src[-1 * LDA_B]); }
; #pragma unroll
;         for (int i = 0; i < 64; ++i) x[i] = bf2f(src[(size_t)i * LDA_B]);
;         __builtin_amdgcn_sched_barrier(0);
; #pragma unroll
;         for (int i = 0; i < 64; ++i) {
;           const float x3 = x[i];
;           x[i] = siluf(w0 * x0 + w1 * x1 + w2 * x2 + w3 * x3) * beta[i];
;           x0 = x1; x1 = x2; x2 = x3;
;         }
	s_mov_b32 s2, 0x9000
	s_nop 0
	v_addc_co_u32_e32 v49, vcc, 0, v3, vcc
	global_load_ushort v56, v[48:49], off offset:1024
	global_load_ushort v57, v[46:47], off
	v_add_co_u32_e32 v46, vcc, s2, v2
	s_mov_b32 s2, 0xa000
	s_nop 0
	v_addc_co_u32_e32 v47, vcc, 0, v3, vcc
	v_add_co_u32_e32 v48, vcc, s2, v2
	global_load_ushort v61, v[46:47], off offset:3072
	s_nop 0
	v_addc_co_u32_e32 v49, vcc, 0, v3, vcc
	global_load_ushort v63, v[48:49], off offset:2048
	v_add_co_u32_e32 v48, vcc, s51, v2
	s_movk_i32 s2, 0x6000
	s_nop 0
	v_addc_co_u32_e32 v49, vcc, 0, v3, vcc
	global_load_ushort v65, v[48:49], off offset:1024
	global_load_ushort v68, v[46:47], off
	v_add_co_u32_e32 v46, vcc, s2, v2
	s_movk_i32 s2, 0x7000
	s_nop 0
	v_addc_co_u32_e32 v47, vcc, 0, v3, vcc
	v_add_co_u32_e32 v48, vcc, s2, v2
	s_movk_i32 s2, 0x5000
	s_nop 0
	v_addc_co_u32_e32 v49, vcc, 0, v3, vcc
	global_load_ushort v72, v[46:47], off offset:3072
	global_load_ushort v73, v[48:49], off offset:2048
	v_add_co_u32_e32 v48, vcc, s2, v2
	s_nop 1
	v_addc_co_u32_e32 v49, vcc, 0, v3, vcc
	global_load_ushort v132, v[48:49], off offset:1024
	global_load_ushort v133, v[46:47], off
	v_add_co_u32_e32 v46, vcc, s81, v2
	s_nop 1
	v_addc_co_u32_e32 v47, vcc, 0, v3, vcc
	v_add_co_u32_e32 v48, vcc, s95, v2
	global_load_ushort v134, v[46:47], off offset:3072
	s_nop 0
	v_addc_co_u32_e32 v49, vcc, 0, v3, vcc
	global_load_ushort v135, v[48:49], off offset:2048
	v_add_co_u32_e32 v48, vcc, s80, v2
	s_nop 1
	v_addc_co_u32_e32 v49, vcc, 0, v3, vcc
	global_load_ushort v136, v[48:49], off offset:1024
	global_load_ushort v137, v[46:47], off
	v_add_co_u32_e32 v46, vcc, s97, v2
	s_nop 1
	v_addc_co_u32_e32 v47, vcc, 0, v3, vcc
	global_load_ushort v142, v[46:47], off offset:2048
	global_load_ushort v144, v[2:3], off offset:3072
	s_waitcnt vmcnt(13)
	v_lshlrev_b32_e32 v58, 16, v58
	v_lshlrev_b32_e32 v59, 16, v59
	v_lshlrev_b32_e32 v67, 16, v67
	v_mov_b32_e32 v66, v59
	v_pk_mul_f32 v[70:71], v[60:61], v[66:67] op_sel_hi:[0,1]
	s_waitcnt vmcnt(10)
	v_lshlrev_b32_e32 v129, 16, v68
	s_waitcnt vmcnt(1)
	v_lshlrev_b32_e32 v143, 16, v142
	s_waitcnt vmcnt(0)
	v_lshlrev_b32_e32 v142, 16, v144
	v_pk_fma_f32 v[58:59], v[0:1], v[58:59], v[70:71] op_sel_hi:[0,1,1]
	v_mov_b32_e32 v68, v67
	v_pk_fma_f32 v[58:59], v[62:63], v[68:69], v[58:59] op_sel_hi:[0,1,1]
	v_mov_b32_e32 v66, v69
	v_mov_b32_e32 v67, v142
	v_pk_fma_f32 v[58:59], v[64:65], v[66:67], v[58:59] op_sel_hi:[0,1,1]
	v_lshlrev_b32_e32 v126, 16, v61
	v_mul_f32_e32 v61, 0xbfb8aa3b, v58
	v_exp_f32_e32 v61, v61
	v_lshlrev_b32_e32 v91, 16, v20
	v_lshlrev_b32_e32 v90, 16, v18
	v_lshlrev_b32_e32 v93, 16, v21
	v_add_f32_e32 v61, 1.0, v61
	v_rcp_f32_e32 v144, v61
	v_mul_f32_e32 v61, 0xbfb8aa3b, v59
	v_exp_f32_e32 v61, v61
	v_lshlrev_b32_e32 v92, 16, v19
	ds_read_b128 v[18:21], v239
	v_lshlrev_b32_e32 v131, 16, v73
	v_add_f32_e32 v61, 1.0, v61
	v_lshlrev_b32_e32 v130, 16, v72
	ds_read_b128 v[70:73], v232
	v_rcp_f32_e32 v145, v61
	v_pk_mul_f32 v[66:67], v[60:61], v[66:67] op_sel_hi:[0,1]
	v_lshlrev_b32_e32 v141, 16, v137
	v_lshlrev_b32_e32 v140, 16, v136
	v_pk_mul_f32 v[58:59], v[58:59], v[144:145]
	v_pk_fma_f32 v[66:67], v[0:1], v[68:69], v[66:67] op_sel_hi:[0,1,1]
	s_waitcnt lgkmcnt(0)
	v_pk_mul_f32 v[58:59], v[58:59], v[70:71]
	v_pk_mov_b32 v[70:71], v[142:143], v[140:141] op_sel:[1,0]
	v_pk_fma_f32 v[66:67], v[62:63], v[142:143], v[66:67] op_sel_hi:[0,1,1]
	v_pk_fma_f32 v[66:67], v[64:65], v[70:71], v[66:67] op_sel_hi:[0,1,1]
	v_mul_f32_e32 v61, 0xbfb8aa3b, v66
	v_exp_f32_e32 v61, v61
	v_lshlrev_b32_e32 v139, 16, v135
	v_lshlrev_b32_e32 v138, 16, v134
	v_lshlrev_b32_e32 v111, 16, v39
	v_add_f32_e32 v61, 1.0, v61
	v_rcp_f32_e32 v68, v61
	v_mul_f32_e32 v61, 0xbfb8aa3b, v67
	v_exp_f32_e32 v61, v61
	v_lshlrev_b32_e32 v110, 16, v38
	v_lshlrev_b32_e32 v113, 16, v41
	v_lshlrev_b32_e32 v112, 16, v40
	v_add_f32_e32 v61, 1.0, v61
	v_rcp_f32_e32 v69, v61
	ds_read_b128 v[38:41], v248
	ds_read_b128 v[134:137], v247
	v_lshlrev_b32_e32 v133, 16, v133
	v_pk_mul_f32 v[66:67], v[66:67], v[68:69]
	v_pk_mul_f32 v[68:69], v[60:61], v[70:71] op_sel_hi:[0,1]
	v_pk_fma_f32 v[68:69], v[0:1], v[142:143], v[68:69] op_sel_hi:[0,1,1]
	v_pk_mul_f32 v[72:73], v[66:67], v[72:73]
	v_pk_mov_b32 v[66:67], v[140:141], v[138:139] op_sel:[1,0]
	v_pk_fma_f32 v[68:69], v[62:63], v[140:141], v[68:69] op_sel_hi:[0,1,1]
	v_pk_fma_f32 v[68:69], v[64:65], v[66:67], v[68:69] op_sel_hi:[0,1,1]
	v_mul_f32_e32 v61, 0xbfb8aa3b, v68
	v_exp_f32_e32 v61, v61
	v_lshlrev_b32_e32 v132, 16, v132
	v_lshlrev_b32_e32 v119, 16, v51
	v_lshlrev_b32_e32 v118, 16, v50
	v_add_f32_e32 v61, 1.0, v61
	v_rcp_f32_e32 v70, v61
	v_mul_f32_e32 v61, 0xbfb8aa3b, v69
	v_exp_f32_e32 v61, v61
	v_lshlrev_b32_e32 v121, 16, v53
	v_lshlrev_b32_e32 v120, 16, v52
	v_lshlrev_b32_e32 v123, 16, v55
	v_add_f32_e32 v61, 1.0, v61
	v_rcp_f32_e32 v71, v61
	v_pk_mul_f32 v[66:67], v[60:61], v[66:67] op_sel_hi:[0,1]
	v_pk_fma_f32 v[66:67], v[0:1], v[140:141], v[66:67] op_sel_hi:[0,1,1]
	v_pk_fma_f32 v[66:67], v[62:63], v[138:139], v[66:67] op_sel_hi:[0,1,1]
	v_pk_mul_f32 v[68:69], v[68:69], v[70:71]
	v_lshlrev_b32_e32 v122, 16, v54
	s_waitcnt lgkmcnt(0)
; DI float siluf(float x) { return x * __builtin_amdgcn_rcpf(1.f + __expf(-x)); }
; DI void phaseB1(const Params& p, int l, char* smem) {
;     ...
; #pragma unroll
;         for (int i = 0; i < 64; ++i) {
;           const float x3 = x[i];
;           x[i] = siluf(w0 * x0 + w1 * x1 + w2 * x2 + w3 * x3) * beta[i];
;           x0 = x1; x1 = x2; x2 = x3;
;         }
	v_pk_mul_f32 v[70:71], v[68:69], v[134:135]
	v_pk_mov_b32 v[134:135], v[138:139], v[132:133] op_sel:[1,0]
	v_lshlrev_b32_e32 v125, 16, v57
	v_pk_fma_f32 v[66:67], v[64:65], v[134:135], v[66:67] op_sel_hi:[0,1,1]
	v_mul_f32_e32 v61, 0xbfb8aa3b, v66
	v_exp_f32_e32 v61, v61
	v_lshlrev_b32_e32 v124, 16, v56
	ds_read_b128 v[50:53], v246
	ds_read_b128 v[54:57], v245
	v_add_f32_e32 v61, 1.0, v61
	v_rcp_f32_e32 v68, v61
	v_mul_f32_e32 v61, 0xbfb8aa3b, v67
	v_exp_f32_e32 v61, v61
	v_lshlrev_b32_e32 v128, 16, v65
	v_lshlrev_b32_e32 v127, 16, v63
	v_lshlrev_b32_e32 v115, 16, v44
	v_add_f32_e32 v61, 1.0, v61
	v_rcp_f32_e32 v69, v61
	v_lshlrev_b32_e32 v114, 16, v42
	v_lshlrev_b32_e32 v117, 16, v45
	v_lshlrev_b32_e32 v116, 16, v43
	v_pk_mul_f32 v[66:67], v[66:67], v[68:69]
	ds_read_b128 v[42:45], v225
	ds_read_b128 v[46:49], v224
	v_pk_mul_f32 v[68:69], v[66:67], v[136:137]
	v_pk_mul_f32 v[66:67], v[60:61], v[134:135] op_sel_hi:[0,1]
	v_pk_fma_f32 v[66:67], v[0:1], v[138:139], v[66:67] op_sel_hi:[0,1,1]
	v_pk_mov_b32 v[136:137], v[132:133], v[130:131] op_sel:[1,0]
	v_pk_fma_f32 v[66:67], v[62:63], v[132:133], v[66:67] op_sel_hi:[0,1,1]
	v_pk_fma_f32 v[66:67], v[64:65], v[136:137], v[66:67] op_sel_hi:[0,1,1]
	v_mul_f32_e32 v61, 0xbfb8aa3b, v66
	v_exp_f32_e32 v61, v61
	v_lshlrev_b32_e32 v103, 16, v31
	v_lshlrev_b32_e32 v102, 16, v30
	v_lshlrev_b32_e32 v105, 16, v33
	v_add_f32_e32 v61, 1.0, v61
	v_rcp_f32_e32 v134, v61
	v_mul_f32_e32 v61, 0xbfb8aa3b, v67
	v_exp_f32_e32 v61, v61
	v_lshlrev_b32_e32 v104, 16, v32
	v_lshlrev_b32_e32 v107, 16, v36
	v_lshlrev_b32_e32 v106, 16, v34
	v_add_f32_e32 v61, 1.0, v61
	v_rcp_f32_e32 v135, v61
	v_lshlrev_b32_e32 v109, 16, v37
	v_lshlrev_b32_e32 v108, 16, v35
	ds_read_b128 v[30:33], v228
	ds_read_b128 v[34:37], v226
	v_pk_mul_f32 v[66:67], v[66:67], v[134:135]
	v_pk_mul_f32 v[134:135], v[60:61], v[136:137] op_sel_hi:[0,1]
	v_pk_fma_f32 v[132:133], v[0:1], v[132:133], v[134:135] op_sel_hi:[0,1,1]
	s_waitcnt lgkmcnt(4)
	v_pk_mul_f32 v[66:67], v[66:67], v[54:55]
	v_pk_mov_b32 v[54:55], v[130:131], v[128:129] op_sel:[1,0]
	v_pk_fma_f32 v[132:133], v[62:63], v[130:131], v[132:133] op_sel_hi:[0,1,1]
	v_pk_fma_f32 v[132:133], v[64:65], v[54:55], v[132:133] op_sel_hi:[0,1,1]
	v_mul_f32_e32 v61, 0xbfb8aa3b, v132
	v_exp_f32_e32 v61, v61
	v_lshlrev_b32_e32 v95, 16, v23
	v_lshlrev_b32_e32 v94, 16, v22
	v_lshlrev_b32_e32 v97, 16, v25
	v_add_f32_e32 v61, 1.0, v61
	v_rcp_f32_e32 v134, v61
	v_mul_f32_e32 v61, 0xbfb8aa3b, v133
	v_exp_f32_e32 v61, v61
	v_lshlrev_b32_e32 v96, 16, v24
	v_lshlrev_b32_e32 v99, 16, v28
	v_lshlrev_b32_e32 v98, 16, v26
	v_add_f32_e32 v61, 1.0, v61
	v_rcp_f32_e32 v135, v61
	v_pk_mul_f32 v[54:55], v[60:61], v[54:55] op_sel_hi:[0,1]
	v_pk_fma_f32 v[54:55], v[0:1], v[130:131], v[54:55] op_sel_hi:[0,1,1]
	v_pk_fma_f32 v[54:55], v[62:63], v[128:129], v[54:55] op_sel_hi:[0,1,1]
	v_pk_mul_f32 v[132:133], v[132:133], v[134:135]
	v_lshlrev_b32_e32 v101, 16, v29
	v_pk_mul_f32 v[56:57], v[132:133], v[56:57]
	v_pk_mov_b32 v[132:133], v[128:129], v[126:127] op_sel:[1,0]
	v_lshlrev_b32_e32 v100, 16, v27
	v_pk_fma_f32 v[54:55], v[64:65], v[132:133], v[54:55] op_sel_hi:[0,1,1]
	v_mul_f32_e32 v61, 0xbfb8aa3b, v54
	v_exp_f32_e32 v61, v61
	ds_read_b128 v[22:25], v231
	ds_read_b128 v[26:29], v229
	v_lshlrev_b32_e32 v83, 16, v12
	v_add_f32_e32 v61, 1.0, v61
	v_rcp_f32_e32 v130, v61
	v_mul_f32_e32 v61, 0xbfb8aa3b, v55
	v_exp_f32_e32 v61, v61
	v_lshlrev_b32_e32 v82, 16, v10
	v_lshlrev_b32_e32 v85, 16, v13
	v_lshlrev_b32_e32 v84, 16, v11
	v_add_f32_e32 v61, 1.0, v61
	v_rcp_f32_e32 v131, v61
	v_lshlrev_b32_e32 v87, 16, v15
	v_lshlrev_b32_e32 v86, 16, v14
	v_lshlrev_b32_e32 v89, 16, v17
	v_pk_mul_f32 v[54:55], v[54:55], v[130:131]
	v_pk_mul_f32 v[130:131], v[60:61], v[132:133] op_sel_hi:[0,1]
	v_pk_fma_f32 v[128:129], v[0:1], v[128:129], v[130:131] op_sel_hi:[0,1,1]
	v_pk_mul_f32 v[54:55], v[54:55], v[50:51]
	v_pk_mov_b32 v[50:51], v[126:127], v[124:125] op_sel:[1,0]
	v_pk_fma_f32 v[128:129], v[62:63], v[126:127], v[128:129] op_sel_hi:[0,1,1]
	v_pk_fma_f32 v[128:129], v[64:65], v[50:51], v[128:129] op_sel_hi:[0,1,1]
	v_mul_f32_e32 v61, 0xbfb8aa3b, v128
	v_exp_f32_e32 v61, v61
	v_lshlrev_b32_e32 v88, 16, v16
	ds_read_b128 v[10:13], v241
	ds_read_b128 v[14:17], v240
	v_add_f32_e32 v61, 1.0, v61
	v_rcp_f32_e32 v130, v61
	v_mul_f32_e32 v61, 0xbfb8aa3b, v129
	v_exp_f32_e32 v61, v61
	v_lshlrev_b32_e32 v74, 16, v5
	v_lshlrev_b32_e32 v75, 16, v7
	v_lshlrev_b32_e32 v79, 16, v6
	v_add_f32_e32 v61, 1.0, v61
	v_rcp_f32_e32 v131, v61
	v_pk_mul_f32 v[50:51], v[60:61], v[50:51] op_sel_hi:[0,1]
	v_pk_fma_f32 v[50:51], v[0:1], v[126:127], v[50:51] op_sel_hi:[0,1,1]
	v_pk_fma_f32 v[50:51], v[62:63], v[124:125], v[50:51] op_sel_hi:[0,1,1]
	v_pk_mul_f32 v[128:129], v[128:129], v[130:131]
	v_lshlrev_b32_e32 v77, 16, v9
	v_pk_mul_f32 v[52:53], v[128:129], v[52:53]
	v_pk_mov_b32 v[128:129], v[124:125], v[122:123] op_sel:[1,0]
	v_lshlrev_b32_e32 v81, 16, v8
	v_pk_fma_f32 v[50:51], v[64:65], v[128:129], v[50:51] op_sel_hi:[0,1,1]
	v_mul_f32_e32 v61, 0xbfb8aa3b, v50
	v_exp_f32_e32 v61, v61
	ds_read_b128 v[2:5], v243
	ds_read_b128 v[6:9], v242
	v_mov_b32_e32 v78, v75
	v_add_f32_e32 v61, 1.0, v61
	v_rcp_f32_e32 v126, v61
	v_mul_f32_e32 v61, 0xbfb8aa3b, v51
	v_exp_f32_e32 v61, v61
	v_mov_b32_e32 v80, v79
	v_mov_b32_e32 v76, v81
	v_add_f32_e32 v61, 1.0, v61
	v_rcp_f32_e32 v127, v61
	s_nop 0
	v_pk_mul_f32 v[50:51], v[50:51], v[126:127]
	v_pk_mul_f32 v[126:127], v[60:61], v[128:129] op_sel_hi:[0,1]
	v_pk_fma_f32 v[124:125], v[0:1], v[124:125], v[126:127] op_sel_hi:[0,1,1]
	s_waitcnt lgkmcnt(8)
; DI float siluf(float x) { return x * __builtin_amdgcn_rcpf(1.f + __expf(-x)); }
; DI void phaseB1(const Params& p, int l, char* smem) {
;     ...
; #pragma unroll
;         for (int i = 0; i < 64; ++i) {
;           const float x3 = x[i];
;           x[i] = siluf(w0 * x0 + w1 * x1 + w2 * x2 + w3 * x3) * beta[i];
;           x0 = x1; x1 = x2; x2 = x3;
;         }
	v_pk_mul_f32 v[50:51], v[50:51], v[46:47]
	v_pk_mov_b32 v[46:47], v[122:123], v[120:121] op_sel:[1,0]
	v_pk_fma_f32 v[124:125], v[62:63], v[122:123], v[124:125] op_sel_hi:[0,1,1]
	v_pk_fma_f32 v[124:125], v[64:65], v[46:47], v[124:125] op_sel_hi:[0,1,1]
	v_mul_f32_e32 v61, 0xbfb8aa3b, v124
	v_exp_f32_e32 v61, v61
	s_nop 0
	v_add_f32_e32 v61, 1.0, v61
	v_rcp_f32_e32 v126, v61
	v_mul_f32_e32 v61, 0xbfb8aa3b, v125
	v_exp_f32_e32 v61, v61
	s_nop 0
	v_add_f32_e32 v61, 1.0, v61
	v_rcp_f32_e32 v127, v61
	v_pk_mul_f32 v[46:47], v[60:61], v[46:47] op_sel_hi:[0,1]
	v_pk_fma_f32 v[46:47], v[0:1], v[122:123], v[46:47] op_sel_hi:[0,1,1]
	v_pk_fma_f32 v[46:47], v[62:63], v[120:121], v[46:47] op_sel_hi:[0,1,1]
	v_pk_mul_f32 v[124:125], v[124:125], v[126:127]
	s_nop 0
	v_pk_mul_f32 v[48:49], v[124:125], v[48:49]
	v_pk_mov_b32 v[124:125], v[120:121], v[118:119] op_sel:[1,0]
	s_nop 0
	v_pk_fma_f32 v[46:47], v[64:65], v[124:125], v[46:47] op_sel_hi:[0,1,1]
	v_mul_f32_e32 v61, 0xbfb8aa3b, v46
	v_exp_f32_e32 v61, v61
	s_nop 0
	v_add_f32_e32 v61, 1.0, v61
	v_rcp_f32_e32 v122, v61
	v_mul_f32_e32 v61, 0xbfb8aa3b, v47
	v_exp_f32_e32 v61, v61
	s_nop 0
	v_add_f32_e32 v61, 1.0, v61
	v_rcp_f32_e32 v123, v61
	s_nop 0
	v_pk_mul_f32 v[46:47], v[46:47], v[122:123]
	v_pk_mul_f32 v[122:123], v[60:61], v[124:125] op_sel_hi:[0,1]
	v_pk_fma_f32 v[120:121], v[0:1], v[120:121], v[122:123] op_sel_hi:[0,1,1]
	v_pk_mul_f32 v[46:47], v[46:47], v[42:43]
	v_pk_mov_b32 v[42:43], v[118:119], v[116:117] op_sel:[1,0]
	v_pk_fma_f32 v[120:121], v[62:63], v[118:119], v[120:121] op_sel_hi:[0,1,1]
	v_pk_fma_f32 v[120:121], v[64:65], v[42:43], v[120:121] op_sel_hi:[0,1,1]
	v_mul_f32_e32 v61, 0xbfb8aa3b, v120
	v_exp_f32_e32 v61, v61
	s_nop 0
	v_add_f32_e32 v61, 1.0, v61
	v_rcp_f32_e32 v122, v61
	v_mul_f32_e32 v61, 0xbfb8aa3b, v121
	v_exp_f32_e32 v61, v61
	s_nop 0
	v_add_f32_e32 v61, 1.0, v61
	v_rcp_f32_e32 v123, v61
	v_pk_mul_f32 v[42:43], v[60:61], v[42:43] op_sel_hi:[0,1]
	v_pk_fma_f32 v[42:43], v[0:1], v[118:119], v[42:43] op_sel_hi:[0,1,1]
	v_pk_fma_f32 v[42:43], v[62:63], v[116:117], v[42:43] op_sel_hi:[0,1,1]
	v_pk_mul_f32 v[120:121], v[120:121], v[122:123]
	s_nop 0
	v_pk_mul_f32 v[44:45], v[120:121], v[44:45]
	v_pk_mov_b32 v[120:121], v[116:117], v[114:115] op_sel:[1,0]
	s_nop 0
	v_pk_fma_f32 v[42:43], v[64:65], v[120:121], v[42:43] op_sel_hi:[0,1,1]
	v_mul_f32_e32 v61, 0xbfb8aa3b, v42
	v_exp_f32_e32 v61, v61
	s_nop 0
	v_add_f32_e32 v61, 1.0, v61
	v_rcp_f32_e32 v118, v61
	v_mul_f32_e32 v61, 0xbfb8aa3b, v43
	v_exp_f32_e32 v61, v61
	s_nop 0
	v_add_f32_e32 v61, 1.0, v61
	v_rcp_f32_e32 v119, v61
	s_nop 0
	v_pk_mul_f32 v[42:43], v[42:43], v[118:119]
	v_pk_mul_f32 v[118:119], v[60:61], v[120:121] op_sel_hi:[0,1]
	v_pk_fma_f32 v[116:117], v[0:1], v[116:117], v[118:119] op_sel_hi:[0,1,1]
	v_pk_mul_f32 v[42:43], v[42:43], v[38:39]
	v_pk_mov_b32 v[38:39], v[114:115], v[112:113] op_sel:[1,0]
	v_pk_fma_f32 v[116:117], v[62:63], v[114:115], v[116:117] op_sel_hi:[0,1,1]
	v_pk_fma_f32 v[116:117], v[64:65], v[38:39], v[116:117] op_sel_hi:[0,1,1]
	v_mul_f32_e32 v61, 0xbfb8aa3b, v116
	v_exp_f32_e32 v61, v61
	s_nop 0
	v_add_f32_e32 v61, 1.0, v61
	v_rcp_f32_e32 v118, v61
	v_mul_f32_e32 v61, 0xbfb8aa3b, v117
	v_exp_f32_e32 v61, v61
	s_nop 0
	v_add_f32_e32 v61, 1.0, v61
	v_rcp_f32_e32 v119, v61
	v_pk_mul_f32 v[38:39], v[60:61], v[38:39] op_sel_hi:[0,1]
	v_pk_fma_f32 v[38:39], v[0:1], v[114:115], v[38:39] op_sel_hi:[0,1,1]
	v_pk_fma_f32 v[38:39], v[62:63], v[112:113], v[38:39] op_sel_hi:[0,1,1]
	v_pk_mul_f32 v[116:117], v[116:117], v[118:119]
	s_nop 0
	v_pk_mul_f32 v[40:41], v[116:117], v[40:41]
	v_pk_mov_b32 v[116:117], v[112:113], v[110:111] op_sel:[1,0]
	s_nop 0
	v_pk_fma_f32 v[38:39], v[64:65], v[116:117], v[38:39] op_sel_hi:[0,1,1]
	v_mul_f32_e32 v61, 0xbfb8aa3b, v38
	v_exp_f32_e32 v61, v61
	s_nop 0
	v_add_f32_e32 v61, 1.0, v61
	v_rcp_f32_e32 v114, v61
	v_mul_f32_e32 v61, 0xbfb8aa3b, v39
	v_exp_f32_e32 v61, v61
	s_nop 0
	v_add_f32_e32 v61, 1.0, v61
	v_rcp_f32_e32 v115, v61
	s_nop 0
	v_pk_mul_f32 v[38:39], v[38:39], v[114:115]
	v_pk_mul_f32 v[114:115], v[60:61], v[116:117] op_sel_hi:[0,1]
	v_pk_fma_f32 v[112:113], v[0:1], v[112:113], v[114:115] op_sel_hi:[0,1,1]
	s_waitcnt lgkmcnt(6)
	v_pk_mul_f32 v[38:39], v[38:39], v[34:35]
	v_pk_mov_b32 v[34:35], v[110:111], v[108:109] op_sel:[1,0]
	v_pk_fma_f32 v[112:113], v[62:63], v[110:111], v[112:113] op_sel_hi:[0,1,1]
	v_pk_fma_f32 v[112:113], v[64:65], v[34:35], v[112:113] op_sel_hi:[0,1,1]
	v_mul_f32_e32 v61, 0xbfb8aa3b, v112
	v_exp_f32_e32 v61, v61
	s_nop 0
	v_add_f32_e32 v61, 1.0, v61
	v_rcp_f32_e32 v114, v61
	v_mul_f32_e32 v61, 0xbfb8aa3b, v113
	v_exp_f32_e32 v61, v61
	s_nop 0
	v_add_f32_e32 v61, 1.0, v61
	v_rcp_f32_e32 v115, v61
	v_pk_mul_f32 v[34:35], v[60:61], v[34:35] op_sel_hi:[0,1]
	v_pk_fma_f32 v[34:35], v[0:1], v[110:111], v[34:35] op_sel_hi:[0,1,1]
	v_pk_fma_f32 v[34:35], v[62:63], v[108:109], v[34:35] op_sel_hi:[0,1,1]
	v_pk_mul_f32 v[112:113], v[112:113], v[114:115]
	s_nop 0
	v_pk_mul_f32 v[36:37], v[112:113], v[36:37]
	v_pk_mov_b32 v[112:113], v[108:109], v[106:107] op_sel:[1,0]
	s_nop 0
	v_pk_fma_f32 v[34:35], v[64:65], v[112:113], v[34:35] op_sel_hi:[0,1,1]
	v_mul_f32_e32 v61, 0xbfb8aa3b, v34
	v_exp_f32_e32 v61, v61
	s_nop 0
	v_add_f32_e32 v61, 1.0, v61
	v_rcp_f32_e32 v110, v61
	v_mul_f32_e32 v61, 0xbfb8aa3b, v35
	v_exp_f32_e32 v61, v61
	s_nop 0
	v_add_f32_e32 v61, 1.0, v61
	v_rcp_f32_e32 v111, v61
	s_nop 0
	v_pk_mul_f32 v[34:35], v[34:35], v[110:111]
	v_pk_mul_f32 v[110:111], v[60:61], v[112:113] op_sel_hi:[0,1]
	v_pk_fma_f32 v[108:109], v[0:1], v[108:109], v[110:111] op_sel_hi:[0,1,1]
	v_pk_mul_f32 v[34:35], v[34:35], v[30:31]
	v_pk_mov_b32 v[30:31], v[106:107], v[104:105] op_sel:[1,0]
	v_pk_fma_f32 v[108:109], v[62:63], v[106:107], v[108:109] op_sel_hi:[0,1,1]
	v_pk_fma_f32 v[108:109], v[64:65], v[30:31], v[108:109] op_sel_hi:[0,1,1]
	v_mul_f32_e32 v61, 0xbfb8aa3b, v108
	v_exp_f32_e32 v61, v61
	s_nop 0
	v_add_f32_e32 v61, 1.0, v61
	v_rcp_f32_e32 v110, v61
	v_mul_f32_e32 v61, 0xbfb8aa3b, v109
	v_exp_f32_e32 v61, v61
	s_nop 0
	v_add_f32_e32 v61, 1.0, v61
	v_rcp_f32_e32 v111, v61
	v_pk_mul_f32 v[30:31], v[60:61], v[30:31] op_sel_hi:[0,1]
	v_pk_fma_f32 v[30:31], v[0:1], v[106:107], v[30:31] op_sel_hi:[0,1,1]
	v_pk_fma_f32 v[30:31], v[62:63], v[104:105], v[30:31] op_sel_hi:[0,1,1]
	v_pk_mul_f32 v[108:109], v[108:109], v[110:111]
	s_nop 0
	v_pk_mul_f32 v[32:33], v[108:109], v[32:33]
	v_pk_mov_b32 v[108:109], v[104:105], v[102:103] op_sel:[1,0]
	s_nop 0
	v_pk_fma_f32 v[30:31], v[64:65], v[108:109], v[30:31] op_sel_hi:[0,1,1]
	v_mul_f32_e32 v61, 0xbfb8aa3b, v30
	v_exp_f32_e32 v61, v61
	s_nop 0
	v_add_f32_e32 v61, 1.0, v61
	v_rcp_f32_e32 v106, v61
	v_mul_f32_e32 v61, 0xbfb8aa3b, v31
	v_exp_f32_e32 v61, v61
	s_nop 0
	v_add_f32_e32 v61, 1.0, v61
	v_rcp_f32_e32 v107, v61
	s_nop 0
	v_pk_mul_f32 v[30:31], v[30:31], v[106:107]
	v_pk_mul_f32 v[106:107], v[60:61], v[108:109] op_sel_hi:[0,1]
	v_pk_fma_f32 v[104:105], v[0:1], v[104:105], v[106:107] op_sel_hi:[0,1,1]
	s_waitcnt lgkmcnt(4)
; DI float siluf(float x) { return x * __builtin_amdgcn_rcpf(1.f + __expf(-x)); }
; DI void phaseB1(const Params& p, int l, char* smem) {
;     ...
; #pragma unroll
;         for (int i = 0; i < 64; ++i) {
;           const float x3 = x[i];
;           x[i] = siluf(w0 * x0 + w1 * x1 + w2 * x2 + w3 * x3) * beta[i];
;           x0 = x1; x1 = x2; x2 = x3;
;         }
	v_pk_mul_f32 v[30:31], v[30:31], v[26:27]
	v_pk_mov_b32 v[26:27], v[102:103], v[100:101] op_sel:[1,0]
	v_pk_fma_f32 v[104:105], v[62:63], v[102:103], v[104:105] op_sel_hi:[0,1,1]
	v_pk_fma_f32 v[104:105], v[64:65], v[26:27], v[104:105] op_sel_hi:[0,1,1]
	v_mul_f32_e32 v61, 0xbfb8aa3b, v104
	v_exp_f32_e32 v61, v61
	s_nop 0
	v_add_f32_e32 v61, 1.0, v61
	v_rcp_f32_e32 v106, v61
	v_mul_f32_e32 v61, 0xbfb8aa3b, v105
	v_exp_f32_e32 v61, v61
	s_nop 0
	v_add_f32_e32 v61, 1.0, v61
	v_rcp_f32_e32 v107, v61
	v_pk_mul_f32 v[26:27], v[60:61], v[26:27] op_sel_hi:[0,1]
	v_pk_fma_f32 v[26:27], v[0:1], v[102:103], v[26:27] op_sel_hi:[0,1,1]
	v_pk_fma_f32 v[26:27], v[62:63], v[100:101], v[26:27] op_sel_hi:[0,1,1]
	v_pk_mul_f32 v[104:105], v[104:105], v[106:107]
	s_nop 0
	v_pk_mul_f32 v[28:29], v[104:105], v[28:29]
	v_pk_mov_b32 v[104:105], v[100:101], v[98:99] op_sel:[1,0]
	s_nop 0
	v_pk_fma_f32 v[26:27], v[64:65], v[104:105], v[26:27] op_sel_hi:[0,1,1]
	v_mul_f32_e32 v61, 0xbfb8aa3b, v26
	v_exp_f32_e32 v61, v61
	s_nop 0
	v_add_f32_e32 v61, 1.0, v61
	v_rcp_f32_e32 v102, v61
	v_mul_f32_e32 v61, 0xbfb8aa3b, v27
	v_exp_f32_e32 v61, v61
	s_nop 0
	v_add_f32_e32 v61, 1.0, v61
	v_rcp_f32_e32 v103, v61
	s_nop 0
	v_pk_mul_f32 v[26:27], v[26:27], v[102:103]
	v_pk_mul_f32 v[102:103], v[60:61], v[104:105] op_sel_hi:[0,1]
	v_pk_fma_f32 v[100:101], v[0:1], v[100:101], v[102:103] op_sel_hi:[0,1,1]
	v_pk_mul_f32 v[26:27], v[26:27], v[22:23]
	v_pk_mov_b32 v[22:23], v[98:99], v[96:97] op_sel:[1,0]
	v_pk_fma_f32 v[100:101], v[62:63], v[98:99], v[100:101] op_sel_hi:[0,1,1]
	v_pk_fma_f32 v[100:101], v[64:65], v[22:23], v[100:101] op_sel_hi:[0,1,1]
	v_mul_f32_e32 v61, 0xbfb8aa3b, v100
	v_exp_f32_e32 v61, v61
	s_nop 0
	v_add_f32_e32 v61, 1.0, v61
	v_rcp_f32_e32 v102, v61
	v_mul_f32_e32 v61, 0xbfb8aa3b, v101
	v_exp_f32_e32 v61, v61
	s_nop 0
	v_add_f32_e32 v61, 1.0, v61
	v_rcp_f32_e32 v103, v61
	v_pk_mul_f32 v[22:23], v[60:61], v[22:23] op_sel_hi:[0,1]
	v_pk_fma_f32 v[22:23], v[0:1], v[98:99], v[22:23] op_sel_hi:[0,1,1]
	v_pk_fma_f32 v[22:23], v[62:63], v[96:97], v[22:23] op_sel_hi:[0,1,1]
	v_pk_mul_f32 v[100:101], v[100:101], v[102:103]
	s_nop 0
	v_pk_mul_f32 v[24:25], v[100:101], v[24:25]
	v_pk_mov_b32 v[100:101], v[96:97], v[94:95] op_sel:[1,0]
	s_nop 0
	v_pk_fma_f32 v[22:23], v[64:65], v[100:101], v[22:23] op_sel_hi:[0,1,1]
	v_mul_f32_e32 v61, 0xbfb8aa3b, v22
	v_exp_f32_e32 v61, v61
	s_nop 0
	v_add_f32_e32 v61, 1.0, v61
	v_rcp_f32_e32 v98, v61
	v_mul_f32_e32 v61, 0xbfb8aa3b, v23
	v_exp_f32_e32 v61, v61
	s_nop 0
	v_add_f32_e32 v61, 1.0, v61
	v_rcp_f32_e32 v99, v61
	s_nop 0
	v_pk_mul_f32 v[22:23], v[22:23], v[98:99]
	v_pk_mul_f32 v[98:99], v[60:61], v[100:101] op_sel_hi:[0,1]
	v_pk_fma_f32 v[96:97], v[0:1], v[96:97], v[98:99] op_sel_hi:[0,1,1]
	v_pk_mul_f32 v[22:23], v[22:23], v[18:19]
	v_pk_mov_b32 v[18:19], v[94:95], v[92:93] op_sel:[1,0]
	v_pk_fma_f32 v[96:97], v[62:63], v[94:95], v[96:97] op_sel_hi:[0,1,1]
	v_pk_fma_f32 v[96:97], v[64:65], v[18:19], v[96:97] op_sel_hi:[0,1,1]
	v_mul_f32_e32 v61, 0xbfb8aa3b, v96
	v_exp_f32_e32 v61, v61
	s_nop 0
	v_add_f32_e32 v61, 1.0, v61
	v_rcp_f32_e32 v98, v61
	v_mul_f32_e32 v61, 0xbfb8aa3b, v97
	v_exp_f32_e32 v61, v61
	s_nop 0
	v_add_f32_e32 v61, 1.0, v61
	v_rcp_f32_e32 v99, v61
	v_pk_mul_f32 v[18:19], v[60:61], v[18:19] op_sel_hi:[0,1]
	v_pk_fma_f32 v[18:19], v[0:1], v[94:95], v[18:19] op_sel_hi:[0,1,1]
	v_pk_fma_f32 v[18:19], v[62:63], v[92:93], v[18:19] op_sel_hi:[0,1,1]
	v_pk_mul_f32 v[96:97], v[96:97], v[98:99]
	s_nop 0
	v_pk_mul_f32 v[20:21], v[96:97], v[20:21]
	v_pk_mov_b32 v[96:97], v[92:93], v[90:91] op_sel:[1,0]
	s_nop 0
	v_pk_fma_f32 v[18:19], v[64:65], v[96:97], v[18:19] op_sel_hi:[0,1,1]
	v_mul_f32_e32 v61, 0xbfb8aa3b, v18
	v_exp_f32_e32 v61, v61
	s_nop 0
	v_add_f32_e32 v61, 1.0, v61
	v_rcp_f32_e32 v94, v61
	v_mul_f32_e32 v61, 0xbfb8aa3b, v19
	v_exp_f32_e32 v61, v61
	s_nop 0
	v_add_f32_e32 v61, 1.0, v61
	v_rcp_f32_e32 v95, v61
	s_nop 0
	v_pk_mul_f32 v[18:19], v[18:19], v[94:95]
	v_pk_mul_f32 v[94:95], v[60:61], v[96:97] op_sel_hi:[0,1]
	v_pk_fma_f32 v[92:93], v[0:1], v[92:93], v[94:95] op_sel_hi:[0,1,1]
	s_waitcnt lgkmcnt(2)
; DI float siluf(float x) { return x * __builtin_amdgcn_rcpf(1.f + __expf(-x)); }
; DI void phaseB1(const Params& p, int l, char* smem) {
;     ...
; #pragma unroll
;         for (int i = 0; i < 64; ++i) {
;           const float x3 = x[i];
;           x[i] = siluf(w0 * x0 + w1 * x1 + w2 * x2 + w3 * x3) * beta[i];
;           x0 = x1; x1 = x2; x2 = x3;
;         }
	v_pk_mul_f32 v[18:19], v[18:19], v[14:15]
	v_pk_mov_b32 v[14:15], v[90:91], v[88:89] op_sel:[1,0]
	v_pk_fma_f32 v[92:93], v[62:63], v[90:91], v[92:93] op_sel_hi:[0,1,1]
	v_pk_fma_f32 v[92:93], v[64:65], v[14:15], v[92:93] op_sel_hi:[0,1,1]
	v_mul_f32_e32 v61, 0xbfb8aa3b, v92
	v_exp_f32_e32 v61, v61
	s_nop 0
	v_add_f32_e32 v61, 1.0, v61
	v_rcp_f32_e32 v94, v61
	v_mul_f32_e32 v61, 0xbfb8aa3b, v93
	v_exp_f32_e32 v61, v61
	s_nop 0
	v_add_f32_e32 v61, 1.0, v61
	v_rcp_f32_e32 v95, v61
	v_pk_mul_f32 v[14:15], v[60:61], v[14:15] op_sel_hi:[0,1]
	v_pk_fma_f32 v[14:15], v[0:1], v[90:91], v[14:15] op_sel_hi:[0,1,1]
	v_pk_fma_f32 v[14:15], v[62:63], v[88:89], v[14:15] op_sel_hi:[0,1,1]
	v_pk_mul_f32 v[92:93], v[92:93], v[94:95]
	s_nop 0
	v_pk_mul_f32 v[16:17], v[92:93], v[16:17]
	v_pk_mov_b32 v[92:93], v[88:89], v[86:87] op_sel:[1,0]
	s_nop 0
	v_pk_fma_f32 v[14:15], v[64:65], v[92:93], v[14:15] op_sel_hi:[0,1,1]
	v_mul_f32_e32 v61, 0xbfb8aa3b, v14
	v_exp_f32_e32 v61, v61
	s_nop 0
	v_add_f32_e32 v61, 1.0, v61
	v_rcp_f32_e32 v90, v61
	v_mul_f32_e32 v61, 0xbfb8aa3b, v15
	v_exp_f32_e32 v61, v61
	s_nop 0
	v_add_f32_e32 v61, 1.0, v61
	v_rcp_f32_e32 v91, v61
	s_nop 0
	v_pk_mul_f32 v[14:15], v[14:15], v[90:91]
	v_pk_mul_f32 v[90:91], v[60:61], v[92:93] op_sel_hi:[0,1]
	v_pk_fma_f32 v[88:89], v[0:1], v[88:89], v[90:91] op_sel_hi:[0,1,1]
	v_pk_mul_f32 v[14:15], v[14:15], v[10:11]
	v_pk_mov_b32 v[10:11], v[86:87], v[84:85] op_sel:[1,0]
	v_pk_fma_f32 v[88:89], v[62:63], v[86:87], v[88:89] op_sel_hi:[0,1,1]
	v_pk_fma_f32 v[88:89], v[64:65], v[10:11], v[88:89] op_sel_hi:[0,1,1]
	v_mul_f32_e32 v61, 0xbfb8aa3b, v88
	v_exp_f32_e32 v61, v61
	s_nop 0
	v_add_f32_e32 v61, 1.0, v61
	v_rcp_f32_e32 v90, v61
	v_mul_f32_e32 v61, 0xbfb8aa3b, v89
	v_exp_f32_e32 v61, v61
	s_nop 0
	v_add_f32_e32 v61, 1.0, v61
	v_rcp_f32_e32 v91, v61
	v_pk_mul_f32 v[10:11], v[60:61], v[10:11] op_sel_hi:[0,1]
	v_pk_fma_f32 v[10:11], v[0:1], v[86:87], v[10:11] op_sel_hi:[0,1,1]
	v_pk_fma_f32 v[10:11], v[62:63], v[84:85], v[10:11] op_sel_hi:[0,1,1]
	v_pk_mul_f32 v[88:89], v[88:89], v[90:91]
	s_nop 0
	v_pk_mul_f32 v[12:13], v[88:89], v[12:13]
	v_pk_mov_b32 v[88:89], v[84:85], v[82:83] op_sel:[1,0]
	s_nop 0
	v_pk_fma_f32 v[10:11], v[64:65], v[88:89], v[10:11] op_sel_hi:[0,1,1]
	v_mul_f32_e32 v61, 0xbfb8aa3b, v10
	v_exp_f32_e32 v61, v61
	s_nop 0
	v_add_f32_e32 v61, 1.0, v61
	v_rcp_f32_e32 v86, v61
	v_mul_f32_e32 v61, 0xbfb8aa3b, v11
	v_exp_f32_e32 v61, v61
	s_nop 0
	v_add_f32_e32 v61, 1.0, v61
	v_rcp_f32_e32 v87, v61
	s_nop 0
	v_pk_mul_f32 v[10:11], v[10:11], v[86:87]
	v_pk_mul_f32 v[86:87], v[60:61], v[88:89] op_sel_hi:[0,1]
	v_pk_fma_f32 v[84:85], v[0:1], v[84:85], v[86:87] op_sel_hi:[0,1,1]
	s_waitcnt lgkmcnt(0)
	v_pk_mul_f32 v[10:11], v[10:11], v[6:7]
	v_pk_mov_b32 v[6:7], v[82:83], v[74:75] op_sel:[1,0]
	v_pk_fma_f32 v[84:85], v[62:63], v[82:83], v[84:85] op_sel_hi:[0,1,1]
	v_pk_fma_f32 v[84:85], v[64:65], v[6:7], v[84:85] op_sel_hi:[0,1,1]
	v_mul_f32_e32 v61, 0xbfb8aa3b, v84
	v_exp_f32_e32 v61, v61
	s_nop 0
	v_add_f32_e32 v61, 1.0, v61
	v_rcp_f32_e32 v86, v61
	v_mul_f32_e32 v61, 0xbfb8aa3b, v85
	v_exp_f32_e32 v61, v61
	s_nop 0
	v_add_f32_e32 v61, 1.0, v61
	v_pk_mul_f32 v[6:7], v[60:61], v[6:7] op_sel_hi:[0,1]
	v_pk_fma_f32 v[6:7], v[0:1], v[82:83], v[6:7] op_sel_hi:[0,1,1]
	v_pk_fma_f32 v[6:7], v[62:63], v[74:75], v[6:7] op_sel_hi:[0,1,1]
	v_pk_fma_f32 v[6:7], v[64:65], v[78:79], v[6:7] op_sel_hi:[0,1,1]
	v_rcp_f32_e32 v87, v61
	v_mul_f32_e32 v61, 0xbfb8aa3b, v6
	v_exp_f32_e32 v61, v61
	v_pk_mul_f32 v[84:85], v[84:85], v[86:87]
	s_nop 0
	v_pk_mul_f32 v[8:9], v[84:85], v[8:9]
	v_add_f32_e32 v61, 1.0, v61
	v_rcp_f32_e32 v82, v61
	v_mul_f32_e32 v61, 0xbfb8aa3b, v7
	v_exp_f32_e32 v61, v61
	s_nop 0
	v_add_f32_e32 v61, 1.0, v61
	v_rcp_f32_e32 v83, v61
	s_nop 0
	v_pk_mul_f32 v[6:7], v[6:7], v[82:83]
	s_nop 0
	v_pk_mul_f32 v[6:7], v[6:7], v[2:3]
	v_pk_mul_f32 v[2:3], v[60:61], v[78:79] op_sel_hi:[0,1]
	v_pk_fma_f32 v[2:3], v[0:1], v[74:75], v[2:3] op_sel_hi:[0,1,1]
	v_pk_fma_f32 v[2:3], v[62:63], v[80:81], v[2:3] op_sel_hi:[0,1,1]
	v_pk_fma_f32 v[2:3], v[64:65], v[76:77], v[2:3] op_sel_hi:[0,1,1]
	v_mul_f32_e32 v0, 0xbfb8aa3b, v2
	v_exp_f32_e32 v0, v0
	s_nop 0
	v_add_f32_e32 v0, 1.0, v0
	v_rcp_f32_e32 v60, v0
	v_mul_f32_e32 v0, 0xbfb8aa3b, v3
	v_exp_f32_e32 v0, v0
	s_nop 0
	v_add_f32_e32 v0, 1.0, v0
	v_rcp_f32_e32 v61, v0
	s_nop 0
	v_pk_mul_f32 v[2:3], v[2:3], v[60:61]
	s_nop 0
	v_pk_mul_f32 v[2:3], v[2:3], v[4:5]
